# XCD barrier: non-leader workgroups wait on the cross-XCD generation word directly (one poll hop fewer)
# speedup vs baseline: 1.0212x; 1.0030x over previous
; __device__ __forceinline__ unsigned xb_ld(unsigned* p)              { return __hip_atomic_load(p, __ATOMIC_RELAXED, __HIP_MEMORY_SCOPE_AGENT); }
; __device__ __forceinline__ unsigned xb_add(unsigned* p, unsigned v) { return __hip_atomic_fetch_add(p, v, __ATOMIC_RELAXED, __HIP_MEMORY_SCOPE_AGENT); }
; #define XB_SPIN(cond, bar) do { unsigned _sp = 0; while (cond) { __builtin_amdgcn_s_sleep(1); \
;     if ((++_sp & 255u) == 0u) { if (xb_ld(&(bar)[XB_TMO])) break; if (_sp > XB_SPIN_CAP) { atomicAdd(&(bar)[XB_TMO], 1u); break; } } } } while (0)
; __device__ __forceinline__ void xcd_barrier(const XcdBarrier& b) {
;     ...
;         if (nloc == 0u) { xcd_barrier_complete(bar, b.x, nloc, nx); b.st[0] = nloc; b.st[1] = nx; }
;         const unsigned old = xb_add(&bar[XB_XSUB(b.x)], 1u);
;         const unsigned gen = old / nloc;
;         if (old + 1u == (gen + 1u) * nloc) {
;     ...
;         } else {
;             XB_SPIN(xb_ld(&bar[XB_XGEN(b.x)]) == gen, bar);
;             __builtin_amdgcn_fence(__ATOMIC_ACQUIRE, "agent");
;             asm volatile("s_waitcnt vmcnt(0)" ::: "memory");
.LBB0_569:
	s_or_b64 exec, exec, s[12:13]
	v_cvt_f32_u32_e32 v5, v3
	s_waitcnt vmcnt(0)
	v_readfirstlane_b32 s10, v4
	v_sub_u32_e32 v4, 0, v3
	v_rcp_iflag_f32_e32 v5, v5
	v_add_u32_e32 v6, s10, v1
	v_mul_f32_e32 v5, 0x4f7ffffe, v5
	v_cvt_u32_f32_e32 v5, v5
	v_mul_lo_u32 v1, v4, v5
	v_mul_hi_u32 v1, v5, v1
	v_add_u32_e32 v1, v5, v1
	v_mul_hi_u32 v1, v6, v1
	v_mul_lo_u32 v4, v1, v3
	v_sub_u32_e32 v4, v6, v4
	v_add_u32_e32 v5, 1, v1
	v_cmp_ge_u32_e32 vcc, v4, v3
	s_nop 1
	v_cndmask_b32_e32 v1, v1, v5, vcc
	v_sub_u32_e32 v5, v4, v3
	v_cndmask_b32_e32 v4, v4, v5, vcc
	v_add_u32_e32 v5, 1, v1
	v_cmp_ge_u32_e32 vcc, v4, v3
	v_add_u32_e32 v4, 1, v6
	s_nop 0
	v_cndmask_b32_e32 v1, v1, v5, vcc
	v_mul_lo_u32 v5, v3, v1
	v_add_u32_e32 v3, v5, v3
	v_cmp_ne_u32_e32 vcc, v4, v3
	s_and_saveexec_b64 s[10:11], vcc
	s_xor_b64 s[12:13], exec, s[10:11]
	s_cbranch_execz .LBB0_583
	buffer_inv sc1
	v_readlane_b32 s10, v255, 15
	v_readlane_b32 s11, v255, 16
	s_waitcnt lgkmcnt(0)
	s_nop 3
	global_load_dword v0, v2, s[10:11] sc1
	s_waitcnt vmcnt(0)
	v_cmp_eq_u32_e32 vcc, v0, v1
	s_and_saveexec_b64 s[38:39], vcc
	s_cbranch_execz .LBB0_582
	s_mov_b32 s10, 1
	s_mov_b64 s[40:41], 0
	s_branch .LBB0_573

; __device__ __forceinline__ unsigned xb_ld(unsigned* p)              { return __hip_atomic_load(p, __ATOMIC_RELAXED, __HIP_MEMORY_SCOPE_AGENT); }
; #define XB_SPIN(cond, bar) do { unsigned _sp = 0; while (cond) { __builtin_amdgcn_s_sleep(1); \
;     if ((++_sp & 255u) == 0u) { if (xb_ld(&(bar)[XB_TMO])) break; if (_sp > XB_SPIN_CAP) { atomicAdd(&(bar)[XB_TMO], 1u); break; } } } } while (0)
; __device__ __forceinline__ void xcd_barrier(const XcdBarrier& b) {
;     ...
;             XB_SPIN(xb_ld(&bar[XB_XGEN(b.x)]) == gen, bar);
.LBB0_577:
	v_readlane_b32 s14, v255, 15
	v_readlane_b32 s15, v255, 16
	s_add_i32 s10, s10, 1
	s_mov_b64 s[46:47], -1
	s_nop 2
	global_load_dword v0, v2, s[14:15] sc1
	s_waitcnt vmcnt(0)
	v_cmp_ne_u32_e32 vcc, v0, v1
	s_orn2_b64 s[44:45], vcc, exec
	s_branch .LBB0_572
